# T3p: tail-queue latency hiding (T3) with a 4-byte pad so all hot loops keep the final's 8-byte code phase
# baseline (speedup 1.0000x reference)
;     __device__ bool next(int i, Unit& u) const { const long L = (long)i * G + c; if (L >= hi) return false; unit_of((int)L, u); return true; }
;     __device__ __forceinline__ void prepare(LAS unsigned char* lds, const pg8::StaticOrder& S, int tid) const {
;         const float* SS = (const float*)(ws + WS_SS);
;         f32x4 p0[9], p1[9];
; #pragma unroll
;         for (int i = 0; i < 9; ++i) {
;             pg8::Unit u; p0[i] = (f32x4){0.f, 0.f, 0.f, 0.f}; p1[i] = p0[i];
;             if (S.next(i, u)) { const float* sp = SS + (size_t)(u.pm * 256 + (tid >> 1)) * 16 + (tid & 1) * 8; p0[i] = *(const f32x4*)sp; p1[i] = *(const f32x4*)(sp + 4); }
;         }
; __global__ void __launch_bounds__(NTHREADS, 2) hymba_fwd(Args a) {
;     ...
;             pg8::Gemm g{(const f16*)(a.ws + WS_XH), (const f16*)(a.ws + WS_W1T) + (size_t)layer * N1 * 1024, MROWS, N1, 1024, nullptr};
;             pg8::StaticOrder S; S.init(MROWS, N1, gridDim.x, blockIdx.x);
;             const bool split = (gridDim.x == 256);
;             if (split) S.hi = 2048;
;             Epi1 E{a.ws, a.qgain + layer * 64, a.kgain + layer * 64};
;             pg8::gemm_phase<Epi1, false>(lds, g, S, E);
.LBB0_166:
	s_andn2_b64 vcc, exec, s[0:1]
	s_cbranch_vccnz .LBB0_384
	v_readlane_b32 s0, v254, 51
	s_load_dword s94, s[86:87], 0x0
	v_readlane_b32 s1, v254, 52
	s_mov_b32 s5, s1
	s_mul_i32 s4, s99, 0x2c0000
	s_lshl_b64 s[0:1], s[4:5], 1
	v_readlane_b32 s4, v254, 2
	s_add_u32 s96, s4, s0
	v_readlane_b32 s0, v254, 3
	s_addc_u32 s97, s0, s1
	s_waitcnt lgkmcnt(0)
	s_cmpk_eq_i32 s94, 0x100
	s_cselect_b64 s[6:7], -1, 0
	s_and_b64 s[0:1], s[6:7], exec
	s_movk_i32 s0, 0x800
	s_cselect_b32 s98, s0, 0x840
	s_mov_b32 s101, 0
	s_nop 0
	s_lshl_b32 s4, s99, 6
	v_writelane_b32 v254, s4, 51
	v_mov_b32_e32 v76, v0
	s_cmp_ge_i32 s2, s98
	v_writelane_b32 v254, s5, 52
	v_readfirstlane_b32 s10, v76
	s_cbranch_scc1 .LBB0_317
	s_waitcnt vmcnt(0)
	v_lshlrev_b32_e32 v2, 5, v76
	v_readlane_b32 s0, v254, 4
	v_and_b32_e32 v194, 32, v2
	v_readlane_b32 s1, v254, 5
	v_ashrrev_i32_e32 v77, 1, v76
	v_writelane_b32 v255, s6, 2
	v_lshl_add_u64 v[74:75], s[0:1], 0, v[194:195]
	v_readlane_b32 s0, v254, 29
	v_writelane_b32 v255, s7, 3
	s_ashr_i32 s4, s94, 31
	v_add_u32_e32 v2, s0, v77
	v_ashrrev_i32_e32 v3, 31, v2
	v_lshlrev_b64 v[2:3], 6, v[2:3]
	v_lshl_add_u64 v[2:3], v[74:75], 0, v[2:3]
	global_load_dwordx4 v[6:9], v[2:3], off offset:16
	global_load_dwordx4 v[10:13], v[2:3], off
	v_readlane_b32 s0, v254, 51
	v_readlane_b32 s1, v254, 52
	v_writelane_b32 v255, s99, 4
	s_mov_b32 s99, s1
	s_add_u32 s0, s94, s2
	s_addc_u32 s1, s4, s3
	v_mov_b64_e32 v[2:3], s[98:99]
	v_cmp_ge_i64_e32 vcc, s[0:1], v[2:3]
	v_mov_b32_e32 v2, 0
	s_and_b64 vcc, exec, vcc
	v_mov_b32_e32 v14, 0
	v_mov_b32_e32 v15, 0
	v_mov_b32_e32 v16, 0
	v_mov_b32_e32 v17, 0
	v_mov_b32_e32 v18, 0
	v_mov_b32_e32 v19, 0
	v_mov_b32_e32 v20, 0
	v_mov_b32_e32 v21, 0
	s_cbranch_vccnz .LBB0_170
	s_ashr_i32 s5, s0, 31
	s_lshr_b32 s5, s5, 29
	s_add_i32 s5, s0, s5
	s_ashr_i32 s6, s5, 3
	s_and_b32 s5, s5, -8
	s_sub_i32 s5, s0, s5
	s_cmp_lt_i32 s5, 0
	s_movk_i32 s7, 0x109
	s_cselect_b32 s7, s7, 0x108
	s_mul_i32 s5, s5, s7
	s_add_i32 s5, s5, s6
	s_mul_hi_i32 s6, s5, 0x2e8ba2e9
	s_lshr_b32 s7, s6, 31
	s_ashr_i32 s6, s6, 3
	s_add_i32 s6, s6, s7
	s_lshl_b32 s7, s6, 2
	s_sub_i32 s8, 0xc0, s7
	s_min_i32 s8, s8, 4
	s_abs_i32 s8, s8
	v_cvt_f32_u32_e32 v3, s8
	s_sub_i32 s9, 0, s8
	s_mul_i32 s6, s6, 44
	s_sub_i32 s5, s5, s6
	v_rcp_iflag_f32_e32 v3, v3
	s_ashr_i32 s6, s5, 31
	s_abs_i32 s5, s5
	v_mul_f32_e32 v3, 0x4f7ffffe, v3
	v_cvt_u32_f32_e32 v3, v3
	s_nop 0
	v_readfirstlane_b32 s11, v3
	s_mul_i32 s9, s9, s11
	s_mul_hi_u32 s9, s11, s9
	s_add_i32 s11, s11, s9
	s_mul_hi_u32 s9, s5, s11
	s_mul_i32 s9, s9, s8
	s_sub_i32 s5, s5, s9
	s_sub_i32 s9, s5, s8
	s_cmp_ge_u32 s5, s8
	s_cselect_b32 s5, s9, s5
	s_sub_i32 s9, s5, s8
	s_cmp_ge_u32 s5, s8
	s_cselect_b32 s5, s9, s5
	s_xor_b32 s5, s5, s6
	s_sub_i32 s5, s5, s6
	s_add_i32 s7, s7, s5
	v_lshl_add_u32 v4, s7, 8, v77
	v_ashrrev_i32_e32 v5, 31, v4
	v_lshlrev_b64 v[4:5], 6, v[4:5]
	v_lshl_add_u64 v[4:5], v[74:75], 0, v[4:5]
	global_load_dwordx4 v[14:17], v[4:5], off
	global_load_dwordx4 v[18:21], v[4:5], off offset:16
